# RWKV serial chain rewritten: in-register state recurrence on 4 chain waves + 4 LDS-DMA loader waves (8-slot ring), one barrier per chunk
# speedup vs baseline: 1.0426x; 1.0426x over previous
.LBB0_406:
	v_and_b32_e32 v1, 63, v0
	v_and_b32_e32 v2, 15, v1
	v_lshrrev_b32_e32 v3, 4, v1
	v_readfirstlane_b32 s6, v0
	s_lshr_b32 s7, s2, 4
	s_and_b32 s8, s2, 15
	s_nop 0
	s_lshr_b32 s6, s6, 6
	s_cmp_gt_u32 s6, 3
	s_cbranch_scc1 .Lser_loader
	v_lshrrev_b32_e32 v4, 1, v3
	v_and_b32_e32 v5, 1, v3
	v_lshlrev_b32_e32 v4, 8, v4
	v_lshl_add_u32 v4, v2, 4, v4
	v_lshl_add_u32 v4, v5, 3, v4
	s_lshl_b32 s12, s6, 4
	v_add_u32_e32 v5, s12, v2
	v_lshlrev_b32_e32 v6, 5, v5
	v_lshl_add_u32 v6, v3, 3, v6
	v_add_u32_e32 v6, 0x2400, v6
	v_lshlrev_b32_e32 v7, 9, v3
	v_lshl_add_u32 v7, v5, 1, v7
	v_add_u32_e32 v7, 0x2c00, v7
	v_lshlrev_b32_e32 v120, 4, v3
	v_add_u32_e32 v120, 0x3400, v120
	v_lshlrev_b32_e32 v116, 13, v3
	v_lshl_add_u32 v116, v5, 1, v116
	s_lshl_b32 s12, s7, 23
	s_lshl_b32 s13, s8, 7
	s_add_u32 s12, s12, s13
	s_add_u32 s12, s12, 0x14a08000
	v_add_u32_e32 v116, s12, v116
	v_mov_b32_e32 v117, 0
	s_mov_b64 s[14:15], 0x1000
	s_mov_b64 s[16:17], 0x8000
	v_lshl_add_u64 v[116:117], v[116:117], 0, s[70:71]
	v_lshl_add_u64 v[118:119], v[116:117], 0, s[14:15]
	v_mov_b32_e32 v8, 0
	v_mov_b32_e32 v9, 0
	v_mov_b32_e32 v10, 0
	v_mov_b32_e32 v11, 0
	v_mov_b32_e32 v12, 0
	v_mov_b32_e32 v13, 0
	v_mov_b32_e32 v14, 0
	v_mov_b32_e32 v15, 0
	v_mov_b32_e32 v16, 0
	v_mov_b32_e32 v17, 0
	v_mov_b32_e32 v18, 0
	v_mov_b32_e32 v19, 0
	v_mov_b32_e32 v20, 0
	v_mov_b32_e32 v21, 0
	v_mov_b32_e32 v22, 0
	v_mov_b32_e32 v23, 0
	v_mov_b32_e32 v24, 0
	v_mov_b32_e32 v25, 0
	v_mov_b32_e32 v26, 0
	v_mov_b32_e32 v27, 0
	v_mov_b32_e32 v28, 0
	v_mov_b32_e32 v29, 0
	v_mov_b32_e32 v30, 0
	v_mov_b32_e32 v31, 0
	s_mov_b32 s10, 0
	s_mov_b32 s11, 0
.Lser_chain_loop:
	s_barrier
	v_add_u32_e32 v121, s10, v4
	v_add_u32_e32 v126, s10, v6
	v_add_u32_e32 v127, s10, v7
	v_add_u32_e32 v128, s10, v120
	v_add_u32_e32 v122, 0x800, v121
	v_add_u32_e32 v123, 0x1000, v121
	v_add_u32_e32 v124, 0x1800, v121
	v_add_u32_e32 v125, 0x2000, v121
	ds_read_b64 v[48:49], v126
	ds_read2_b64 v[32:35], v121 offset1:64
	ds_read2_b64 v[36:39], v121 offset0:128 offset1:192
	ds_read2_b64 v[40:43], v122 offset1:64
	ds_read2_b64 v[44:47], v122 offset0:128 offset1:192
	ds_read_b128 v[82:85], v128
	ds_read_b128 v[86:89], v128 offset:64
	ds_read_b128 v[90:93], v128 offset:128
	ds_read_b128 v[94:97], v128 offset:192
	ds_read_u16 v133, v127
	ds_read_u16 v134, v127 offset:128
	ds_read_u16 v135, v127 offset:256
	ds_read_u16 v136, v127 offset:384
	ds_read2_b64 v[62:65], v123 offset1:64
	ds_read2_b64 v[66:69], v123 offset0:128 offset1:192
	ds_read2_b64 v[70:73], v124 offset1:64
	ds_read2_b64 v[74:77], v124 offset0:128 offset1:192
	ds_read2_b64 v[78:81], v125 offset1:64
	s_waitcnt lgkmcnt(0)
	v_lshl_or_b32 v60, v134, 16, v133
	v_lshl_or_b32 v61, v136, 16, v135
	v_lshlrev_b32_e32 v50, 16, v48
	v_and_b32_e32 v51, 0xffff0000, v48
	v_lshlrev_b32_e32 v52, 16, v49
	v_and_b32_e32 v53, 0xffff0000, v49
	v_pk_mul_f32 v[98:99], v[8:9], v[82:83]
	v_pk_mul_f32 v[100:101], v[10:11], v[84:85]
	v_pk_mul_f32 v[102:103], v[12:13], v[86:87]
	v_pk_mul_f32 v[104:105], v[14:15], v[88:89]
	v_pk_mul_f32 v[106:107], v[16:17], v[90:91]
	v_pk_mul_f32 v[108:109], v[18:19], v[92:93]
	v_pk_mul_f32 v[110:111], v[20:21], v[94:95]
	v_pk_mul_f32 v[112:113], v[22:23], v[96:97]
	v_mfma_f32_16x16x32_bf16 v[50:53], v[32:35], v[24:27], v[50:53]
	v_mfma_f32_16x16x32_bf16 v[50:53], v[36:39], v[28:31], v[50:53]
	v_mfma_f32_16x16x32_bf16 v[54:57], v[40:43], v[24:27], 0
	v_mfma_f32_16x16x32_bf16 v[54:57], v[44:47], v[28:31], v[54:57]
	s_nop 5
	v_cvt_pk_bf16_f32 v58, v50, v51
	v_cvt_pk_bf16_f32 v59, v52, v53
	s_nop 1
	v_mfma_f32_16x16x32_bf16 v[8:11], v[62:65], v[58:61], v[98:101]
	v_mfma_f32_16x16x32_bf16 v[12:15], v[66:69], v[58:61], v[102:105]
	v_mfma_f32_16x16x32_bf16 v[16:19], v[70:73], v[58:61], v[106:109]
	v_mfma_f32_16x16x32_bf16 v[20:23], v[74:77], v[58:61], v[110:113]
	v_mfma_f32_16x16x32_bf16 v[54:57], v[78:81], v[58:61], v[54:57]
	s_nop 3
	v_cvt_pk_bf16_f32 v24, v8, v9
	v_cvt_pk_bf16_f32 v25, v10, v11
	v_cvt_pk_bf16_f32 v26, v12, v13
	v_cvt_pk_bf16_f32 v27, v14, v15
	v_cvt_pk_bf16_f32 v28, v16, v17
	v_cvt_pk_bf16_f32 v29, v18, v19
	v_cvt_pk_bf16_f32 v30, v20, v21
	v_cvt_pk_bf16_f32 v31, v22, v23
	v_cvt_pk_bf16_f32 v114, v54, v54
	v_cvt_pk_bf16_f32 v115, v55, v55
	v_cvt_pk_bf16_f32 v131, v56, v56
	v_cvt_pk_bf16_f32 v132, v57, v57
	global_store_short v[116:117], v114, off
	global_store_short v[116:117], v115, off offset:2048
	global_store_short v[118:119], v131, off
	global_store_short v[118:119], v132, off offset:2048
	v_lshl_add_u64 v[116:117], v[116:117], 0, s[16:17]
	v_lshl_add_u64 v[118:119], v[118:119], 0, s[16:17]
	s_add_u32 s10, s10, 0x3800
	s_cmp_eq_u32 s10, 0x1c000
	s_cselect_b32 s10, 0, s10
	s_add_u32 s11, s11, 1
	s_cmp_lt_u32 s11, 0x100
	s_cbranch_scc1 .Lser_chain_loop
	s_branch .Lser_exit
.Lser_loader:
	s_sub_u32 s9, s6, 4
	v_lshrrev_b32_e32 v4, 4, v1
	v_lshrrev_b32_e32 v5, 3, v1
	v_and_b32_e32 v6, 7, v1
	s_lshl_b32 s30, s7, 24
	s_lshl_b32 s31, s8, 8
	s_add_u32 s30, s30, s31
	s_mul_i32 s72, s7, 0x1800000
	s_lshl_b32 s73, s8, 7
	s_add_u32 s72, s72, s73
	s_cmp_eq_u32 s9, 0
	s_cbranch_scc1 .Lser_role0
	s_cmp_eq_u32 s9, 1
	s_cbranch_scc1 .Lser_role1
	s_cmp_eq_u32 s9, 2
	s_cbranch_scc1 .Lser_role2
	v_mul_u32_u24_e32 v10, 0x1800, v5
	v_lshl_add_u32 v10, v6, 4, v10
	v_mov_b32_e32 v11, v10
	v_mov_b32_e32 v12, v10
	v_mov_b32_e32 v13, v10
	s_add_u32 s12, s68, s72
	s_addc_u32 s13, s69, 0
	s_add_u32 s12, s12, 0x1000
	s_addc_u32 s13, s13, 0
	s_add_u32 s14, s12, 0xc000
	s_addc_u32 s15, s13, 0
	s_mov_b64 s[16:17], s[12:13]
	s_mov_b64 s[18:19], s[14:15]
	s_mov_b32 s20, 0x18000
	s_mov_b32 s21, 0x18000
	s_mov_b32 s22, 0x18000
	s_mov_b32 s23, 0x18000
	s_mov_b32 s24, 0x2c00
	s_mov_b32 s25, 0x3000
	s_mov_b32 s26, 0x2c00
	s_mov_b32 s27, 0x3000
	s_branch .Lser_ld_go
.Lser_role0:
	v_lshlrev_b32_e32 v10, 12, v2
	v_lshl_add_u32 v10, v4, 4, v10
	v_mov_b32_e32 v11, v10
	v_mov_b32_e32 v12, v10
	v_mov_b32_e32 v13, v10
	s_add_u32 s12, s70, s30
	s_addc_u32 s13, s71, 0
	s_add_u32 s12, s12, 0x7900000
	s_addc_u32 s13, s13, 0
	s_add_u32 s14, s12, 0x40
	s_addc_u32 s15, s13, 0
	s_add_u32 s16, s12, 0x80
	s_addc_u32 s17, s13, 0
	s_add_u32 s18, s12, 0xc0
	s_addc_u32 s19, s13, 0
	s_mov_b32 s20, 0x10000
	s_mov_b32 s21, 0x10000
	s_mov_b32 s22, 0x10000
	s_mov_b32 s23, 0x10000
	s_mov_b32 s24, 0x0
	s_mov_b32 s25, 0x400
	s_mov_b32 s26, 0x800
	s_mov_b32 s27, 0xc00
	s_branch .Lser_ld_go
.Lser_role1:
	v_lshrrev_b32_e32 v10, 2, v2
	v_lshlrev_b32_e32 v10, 12, v10
	v_and_b32_e32 v11, 3, v2
	v_lshl_add_u32 v10, v11, 6, v10
	v_lshl_add_u32 v10, v4, 4, v10
	v_mov_b32_e32 v11, v10
	v_mov_b32_e32 v12, v10
	v_mov_b32_e32 v13, v10
	s_add_u32 s12, s70, s30
	s_addc_u32 s13, s71, 0
	s_add_u32 s12, s12, 0x9900000
	s_addc_u32 s13, s13, 0
	s_add_u32 s14, s12, 0x4000
	s_addc_u32 s15, s13, 0
	s_add_u32 s16, s12, 0x8000
	s_addc_u32 s17, s13, 0
	s_add_u32 s18, s12, 0xc000
	s_addc_u32 s19, s13, 0
	s_mov_b32 s20, 0x10000
	s_mov_b32 s21, 0x10000
	s_mov_b32 s22, 0x10000
	s_mov_b32 s23, 0x10000
	s_mov_b32 s24, 0x1000
	s_mov_b32 s25, 0x1400
	s_mov_b32 s26, 0x1800
	s_mov_b32 s27, 0x1c00
	s_branch .Lser_ld_go
.Lser_role2:
	v_mul_u32_u24_e32 v10, 0x1800, v2
	v_lshl_add_u32 v10, v4, 4, v10
	v_mul_u32_u24_e32 v11, 0x1800, v5
	v_lshl_add_u32 v11, v6, 4, v11
	v_mov_b32_e32 v12, v11
	v_lshlrev_b32_e32 v13, 4, v2
	s_add_u32 s12, s68, s72
	s_addc_u32 s13, s69, 0
	s_add_u32 s14, s12, 0x800
	s_addc_u32 s15, s13, 0
	s_add_u32 s16, s14, 0xc000
	s_addc_u32 s17, s15, 0
	s_lshl_b32 s73, s2, 16
	s_add_u32 s18, s70, s73
	s_addc_u32 s19, s71, 0
	s_add_u32 s18, s18, 0x15a08000
	s_addc_u32 s19, s19, 0
	s_mov_b32 s20, 0x18000
	s_mov_b32 s21, 0x18000
	s_mov_b32 s22, 0x18000
	s_mov_b32 s23, 0x100
	s_mov_b32 s24, 0x2000
	s_mov_b32 s25, 0x2400
	s_mov_b32 s26, 0x2800
	s_mov_b32 s27, 0x3400
.Lser_ld_go:
	s_mov_b32 s28, 0
	s_mov_b32 s29, 0
.Lser_ld_pro:
	s_cmp_lt_u32 s29, 0xff
	s_cselect_b32 s72, s20, 0
	s_cselect_b32 s73, s21, 0
	s_cselect_b32 s74, s22, 0
	s_cselect_b32 s75, s23, 0
	s_add_u32 m0, s28, s24
	s_nop 0
	global_load_lds_dwordx4 v10, s[12:13]
	s_add_u32 s12, s12, s72
	s_addc_u32 s13, s13, 0
	s_add_u32 m0, s28, s25
	s_nop 0
	global_load_lds_dwordx4 v11, s[14:15]
	s_add_u32 s14, s14, s73
	s_addc_u32 s15, s15, 0
	s_add_u32 m0, s28, s26
	s_nop 0
	global_load_lds_dwordx4 v12, s[16:17]
	s_add_u32 s16, s16, s74
	s_addc_u32 s17, s17, 0
	s_add_u32 m0, s28, s27
	s_nop 0
	global_load_lds_dwordx4 v13, s[18:19]
	s_add_u32 s18, s18, s75
	s_addc_u32 s19, s19, 0
	s_add_u32 s28, s28, 0x3800
	s_cmp_eq_u32 s28, 0x1c000
	s_cselect_b32 s28, 0, s28
	s_add_u32 s29, s29, 1
	s_cmp_lt_u32 s29, 7
	s_cbranch_scc1 .Lser_ld_pro
	s_mov_b32 s3, 0
.Lser_ld_loop:
	s_waitcnt vmcnt(24)
	s_barrier
	s_cmp_lt_u32 s29, 0xff
	s_cselect_b32 s72, s20, 0
	s_cselect_b32 s73, s21, 0
	s_cselect_b32 s74, s22, 0
	s_cselect_b32 s75, s23, 0
	s_add_u32 m0, s28, s24
	s_nop 0
	global_load_lds_dwordx4 v10, s[12:13]
	s_add_u32 s12, s12, s72
	s_addc_u32 s13, s13, 0
	s_add_u32 m0, s28, s25
	s_nop 0
	global_load_lds_dwordx4 v11, s[14:15]
	s_add_u32 s14, s14, s73
	s_addc_u32 s15, s15, 0
	s_add_u32 m0, s28, s26
	s_nop 0
	global_load_lds_dwordx4 v12, s[16:17]
	s_add_u32 s16, s16, s74
	s_addc_u32 s17, s17, 0
	s_add_u32 m0, s28, s27
	s_nop 0
	global_load_lds_dwordx4 v13, s[18:19]
	s_add_u32 s18, s18, s75
	s_addc_u32 s19, s19, 0
	s_add_u32 s28, s28, 0x3800
	s_cmp_eq_u32 s28, 0x1c000
	s_cselect_b32 s28, 0, s28
	s_add_u32 s29, s29, 1
	s_add_u32 s3, s3, 1
	s_cmp_lt_u32 s3, 0x100
	s_cbranch_scc1 .Lser_ld_loop
	s_waitcnt vmcnt(0)
.Lser_exit:
	v_lshlrev_b32_e32 v157, 2, v0
